# v47 + mLSTM piece 1 state-update: ten LDS operand reads issued up front into spare VGPRs (was five serial round trips)
# baseline (speedup 1.0000x reference)
; #define LAS __attribute__((address_space(3)))
; __device__ __forceinline__ f32x4 mfma16(bf16x8 a, bf16x8 b, f32x4 c) { return __builtin_amdgcn_mfma_f32_16x16x32_bf16(a, b, c, 0, 0, 0); }
; __device__ __forceinline__ void lds_barrier() { asm volatile("s_waitcnt lgkmcnt(0)" ::: "memory"); __builtin_amdgcn_s_barrier(); asm volatile("" ::: "memory"); }
; __device__ __forceinline__ void mlstm_item(const P& p, const Ctx& c, int seg, int w, bool save) {
;     ...
;         const float gtot = gtotp[0];
; #pragma unroll
;         for (int j = 0; j < 12; ++j) C[j] *= gtot;
;         f32x4 Sa[2], Ia[2]; Sa[0] = Sa[1] = Ia[0] = Ia[1] = (f32x4){0.f, 0.f, 0.f, 0.f};
;         float qnacc = 0.f;
; #pragma unroll
;         for (int pp = 0; pp < 3; ++pp) {
;             const int d0 = pp * 128;
;             __builtin_amdgcn_sched_barrier(0);
;             asm volatile("" : "+v"(tidv));
;             lds_barrier();
; #pragma unroll
;             for (int r = 0; r < 2; ++r) { const int id = tidv + 512 * r;
;                 { const int i = id >> 4, c8 = (id & 15) * 8; *(LAS u32x4*)(Qs + i * 136 + c8) = pq[r]; *(LAS u32x4*)(Ks + i * 136 + c8) = pk[r]; }
;                 { const int dd = id >> 3, c8 = (id & 7) * 8; *(LAS u32x4*)(KTs + dd * 72 + c8) = pt[r]; } }
;             lds_barrier();
;             if (pp < 2) gl_piece(ch, pp + 1, tidv); else if (ch + 1 < 8) gl_piece(ch + 1, 0, tidv);
;             { const int tm = c.wv >> 1, tn0 = (c.wv & 1) * 2;
; #pragma unroll
;               for (int kk = 0; kk < 4; ++kk) { const bf16x8 a = *(const LAS bf16x8*)(Qs + (tm * 16 + l15) * 136 + kk * 32 + quad * 8);
; #pragma unroll
;                   for (int x = 0; x < 2; ++x) { const int tn = tn0 + x;
;                       const bf16x8 bk = *(const LAS bf16x8*)(Ks + (tn * 16 + l15) * 136 + kk * 32 + quad * 8);
;                       const bf16x8 bc = *(const LAS bf16x8*)(Cimg + (tn * 16 + l15) * 392 + d0 + kk * 32 + quad * 8);
;                       Sa[x] = mfma16(a, bk, Sa[x]); Ia[x] = mfma16(a, bc, Ia[x]); } } }
.LBB0_373:
	v_mov_b32_e32 v4, s62
	ds_read_b32 v182, v4
	v_add_u32_e32 v4, s79, v180
	v_lshlrev_b32_e32 v116, 4, v181
	v_mul_lo_u32 v4, v4, s63
	v_add_u32_e32 v86, 0, v116
	s_waitcnt lgkmcnt(0)
	v_pk_mul_f32 v[8:9], v[8:9], v[182:183] op_sel_hi:[1,0]
	v_pk_mul_f32 v[6:7], v[6:7], v[182:183] op_sel_hi:[1,0]
	v_pk_mul_f32 v[16:17], v[16:17], v[182:183] op_sel_hi:[1,0]
	v_pk_mul_f32 v[14:15], v[14:15], v[182:183] op_sel_hi:[1,0]
	v_pk_mul_f32 v[24:25], v[24:25], v[182:183] op_sel_hi:[1,0]
	v_pk_mul_f32 v[22:23], v[22:23], v[182:183] op_sel_hi:[1,0]
	v_pk_mul_f32 v[28:29], v[28:29], v[182:183] op_sel_hi:[1,0]
	v_pk_mul_f32 v[26:27], v[26:27], v[182:183] op_sel_hi:[1,0]
	v_add_u32_e32 v82, s50, v116
	v_add3_u32 v152, s29, v4, v116
	v_add_u32_e32 v117, s78, v180
	s_waitcnt lgkmcnt(0)
	s_barrier
	v_lshlrev_b32_e32 v4, 3, v191
	v_and_b32_e32 v100, 0x78, v4
	v_lshlrev_b32_e32 v4, 1, v100
	v_ashrrev_i32_e32 v94, 4, v191
	v_add_u32_e32 v83, 0, v4
	v_add_u32_e32 v84, s50, v4
	v_lshlrev_b32_e32 v4, 4, v191
	v_mul_lo_u32 v85, v94, s38
	v_and_b32_e32 v124, 0x70, v4
	v_add_u32_e32 v87, v83, v85
	v_add_u32_e32 v4, s18, v124
	s_waitcnt vmcnt(5)
	ds_write_b128 v87, v[58:61] offset:50176
	v_add_u32_e32 v58, v84, v85
	v_ashrrev_i32_e32 v122, 3, v191
	s_waitcnt vmcnt(4)
	ds_write_b128 v58, v[62:65]
	v_mad_u64_u32 v[58:59], s[16:17], v122, s63, v[4:5]
	s_waitcnt vmcnt(3)
	ds_write_b128 v58, v[66:69]
	v_add_u32_e32 v58, 0x200, v191
	v_ashrrev_i32_e32 v114, 4, v58
	v_mul_lo_u32 v59, v114, s38
	v_add_u32_e32 v60, v83, v59
	v_add_u32_e32 v59, v84, v59
	v_ashrrev_i32_e32 v118, 3, v58
	s_waitcnt vmcnt(1)
	ds_write_b128 v59, v[74:77]
	v_mad_u64_u32 v[58:59], s[16:17], v118, s63, v[4:5]
	v_add_u32_e32 v4, s21, v180
	ds_write_b128 v60, v[70:73] offset:50176
	s_waitcnt vmcnt(0)
	ds_write_b128 v58, v[78:81]
	v_mul_lo_u32 v4, v4, s38
	s_waitcnt lgkmcnt(0)
	s_barrier
	v_add_u32_e32 v157, v86, v4
	ds_read_b128 v[58:61], v157 offset:50176
	v_add_u32_e32 v193, s20, v180
	v_mul_lo_u32 v4, v193, s38
	v_add_u32_e32 v158, v82, v4
	ds_read_b128 v[62:65], v158
	v_mul_lo_u32 v4, v193, s33
	v_add_u32_e32 v194, s39, v180
	v_add_u32_e32 v155, v86, v4
	v_mul_lo_u32 v4, v194, s38
	v_add_u32_e32 v156, v82, v4
	v_mul_lo_u32 v4, v194, s33
	ds_read_b128 v[66:69], v155
	ds_read_b128 v[70:73], v157 offset:50240
	ds_read_b128 v[74:77], v158 offset:64
	ds_read_b128 v[78:81], v155 offset:64
	ds_read_b128 v[82:85], v156
	v_add_u32_e32 v153, v86, v4
	s_add_u32 s86, s68, s84
	ds_read_b128 v[86:89], v153
	ds_read_b128 v[90:93], v156 offset:64
	v_ashrrev_i32_e32 v95, 31, v94
	s_waitcnt lgkmcnt(7)
	v_mfma_f32_16x16x32_bf16 v[62:65], v[58:61], v[62:65], 0
	s_addc_u32 s87, s69, s85
	v_lshl_add_u64 v[94:95], s[86:87], 0, v[94:95]
	v_lshl_add_u64 v[98:99], v[94:95], 0, s[60:61]
	v_or_b32_e32 v4, s46, v100
	s_waitcnt lgkmcnt(6)
	v_mfma_f32_16x16x32_bf16 v[66:69], v[58:61], v[66:69], 0
	ds_read_b128 v[94:97], v153 offset:64
	v_ashrrev_i32_e32 v123, 31, v122
	v_lshlrev_b64 v[106:107], 10, v[122:123]
	s_waitcnt lgkmcnt(3)
	v_mfma_f32_16x16x32_bf16 v[82:85], v[58:61], v[82:85], 0
	v_or_b32_e32 v106, v106, v124
	s_mov_b32 s41, 0xff420000
	v_ashrrev_i32_e32 v115, 31, v114
	s_waitcnt lgkmcnt(2)
	v_mfma_f32_16x16x32_bf16 v[58:61], v[58:61], v[86:89], 0
	v_mad_u64_u32 v[86:87], s[16:17], v98, s58, v[4:5]
	v_ashrrev_i32_e32 v119, 31, v118
	v_mfma_f32_16x16x32_bf16 v[62:65], v[70:73], v[74:77], v[62:65]
	v_mov_b32_e32 v74, v87
	v_mad_u64_u32 v[74:75], s[16:17], v99, s58, v[74:75]
	v_mov_b32_e32 v87, v74
	v_lshlrev_b64 v[74:75], 1, v[86:87]
	ds_read_b128 v[86:89], v157 offset:50304
	v_mfma_f32_16x16x32_bf16 v[66:69], v[70:73], v[78:81], v[66:69]
	v_lshl_add_u64 v[78:79], s[72:73], 0, v[74:75]
	v_lshl_add_u64 v[98:99], s[74:75], 0, v[74:75]
	ds_read_b128 v[74:77], v158 offset:128
	s_waitcnt lgkmcnt(3)
	v_mfma_f32_16x16x32_bf16 v[82:85], v[70:73], v[90:93], v[82:85]
	s_add_u32 s16, s82, s40
	s_addc_u32 s17, s83, s35
	v_and_b32_e32 v146, 3, v191
	s_waitcnt lgkmcnt(2)
	v_mfma_f32_16x16x32_bf16 v[58:61], v[70:73], v[94:97], v[58:61]
	ds_read_b128 v[70:73], v155 offset:128
	ds_read_b128 v[90:93], v157 offset:50368
	ds_read_b128 v[94:97], v158 offset:192
	v_lshlrev_b32_e32 v123, 5, v146
	v_lshl_add_u32 v130, v146, 6, 0
	s_waitcnt lgkmcnt(3)
	v_mfma_f32_16x16x32_bf16 v[62:65], v[86:89], v[74:77], v[62:65]
	global_load_dwordx4 v[78:81], v[78:79], off
	s_nop 0
	global_load_dwordx4 v[74:77], v[98:99], off
	ds_read_b128 v[98:101], v156 offset:128
	ds_read_b128 v[102:105], v155 offset:192
	v_add_u32_e32 v142, 0x20200, v130
	s_waitcnt lgkmcnt(4)
	v_mfma_f32_16x16x32_bf16 v[66:69], v[86:89], v[70:73], v[66:69]
	ds_read_b128 v[70:73], v153 offset:128
	ds_read_b128 v[110:113], v156 offset:192
	s_waitcnt lgkmcnt(3)
	v_mfma_f32_16x16x32_bf16 v[82:85], v[86:89], v[98:101], v[82:85]
	ds_read_b128 v[98:101], v153 offset:192
	s_waitcnt lgkmcnt(2)
; #define LAS __attribute__((address_space(3)))
; __device__ __forceinline__ void mlstm_item(const P& p, const Ctx& c, int seg, int w, bool save) {
;     ...
;             { const bf16x8 va0 = *(const LAS bf16x8*)(VWs + (e16 * 16 + l15) * 72 + quad * 8), va1 = *(const LAS bf16x8*)(VWs + (e16 * 16 + l15) * 72 + 32 + quad * 8);
; #pragma unroll
;               for (int jl = 0; jl < 4; ++jl) { const int ntl = 2 * jl + par, j = pp * 4 + jl;
;                   C[j] = mfma16(va0, *(const LAS bf16x8*)(KTs + (ntl * 16 + l15) * 72 + quad * 8), C[j]);
;                   C[j] = mfma16(va1, *(const LAS bf16x8*)(KTs + (ntl * 16 + l15) * 72 + 32 + quad * 8), C[j]); } }
;             { const int t = tidv >> 3, part = tidv & 7;
;               const u32x4 q0 = *(const LAS u32x4*)(Qs + t * 136 + part * 16), q1 = *(const LAS u32x4*)(Qs + t * 136 + part * 16 + 8);
;               const LAS float* np = nold + d0 + part * 16; const f32x4 n0 = *(const LAS f32x4*)np, n1 = *(const LAS f32x4*)(np + 4), n2 = *(const LAS f32x4*)(np + 8), n3 = *(const LAS f32x4*)(np + 12);
;               qnacc += bflo(q0.x) * n0[0] + bfhi(q0.x) * n0[1] + bflo(q0.y) * n0[2] + bfhi(q0.y) * n0[3] + bflo(q0.z) * n1[0] + bfhi(q0.z) * n1[1] + bflo(q0.w) * n1[2] + bfhi(q0.w) * n1[3]
;                      + bflo(q1.x) * n2[0] + bfhi(q1.x) * n2[1] + bflo(q1.y) * n2[2] + bfhi(q1.y) * n2[3] + bflo(q1.z) * n3[0] + bfhi(q1.z) * n3[1] + bflo(q1.w) * n3[2] + bfhi(q1.w) * n3[3]; }
;             { const int dd = tidv >> 2, part = tidv & 3;
;               const u32x4 k0 = *(const LAS u32x4*)(KTs + dd * 72 + part * 16), k1 = *(const LAS u32x4*)(KTs + dd * 72 + part * 16 + 8);
;               const LAS float* wp = wgt + part * 16; const f32x4 w0 = *(const LAS f32x4*)wp, w1 = *(const LAS f32x4*)(wp + 4), w2 = *(const LAS f32x4*)(wp + 8), w3 = *(const LAS f32x4*)(wp + 12);
;               float a = bflo(k0.x) * w0[0] + bfhi(k0.x) * w0[1] + bflo(k0.y) * w0[2] + bfhi(k0.y) * w0[3] + bflo(k0.z) * w1[0] + bfhi(k0.z) * w1[1] + bflo(k0.w) * w1[2] + bfhi(k0.w) * w1[3]
;                       + bflo(k1.x) * w2[0] + bfhi(k1.x) * w2[1] + bflo(k1.y) * w2[2] + bfhi(k1.y) * w2[3] + bflo(k1.z) * w3[0] + bfhi(k1.z) * w3[1] + bflo(k1.w) * w3[2] + bfhi(k1.w) * w3[3];
;               a = dpp_add<0xB1>(a); a = dpp_add<0x4E>(a);
;               if (part == 0) nnew[d0 + dd] = gtot * nold[d0 + dd] + a; }
	v_mfma_f32_16x16x32_bf16 v[58:61], v[86:89], v[70:73], v[58:61]
	v_lshl_add_u64 v[70:71], s[16:17], 0, v[106:107]
	v_add_co_u32_e32 v70, vcc, s41, v70
	v_mfma_f32_16x16x32_bf16 v[62:65], v[90:93], v[94:97], v[62:65]
	s_nop 0
	v_addc_co_u32_e32 v71, vcc, -1, v71, vcc
	global_load_dwordx4 v[106:109], v[70:71], off offset:-128
	v_mfma_f32_16x16x32_bf16 v[70:73], v[90:93], v[102:105], v[66:69]
	s_nop 2
	v_lshl_add_u64 v[66:67], s[86:87], 0, v[114:115]
	v_lshl_add_u64 v[94:95], v[66:67], 0, s[60:61]
	s_waitcnt lgkmcnt(1)
	v_mfma_f32_16x16x32_bf16 v[66:69], v[90:93], v[110:113], v[82:85]
	s_nop 2
	v_mul_lo_u32 v250, v117, s63
	v_add3_u32 v154, s18, v250, v116
	ds_read_b128 v[82:85], v152
	ds_read_b128 v[86:89], v152 offset:64
	ds_read_b128 v[208:211], v154
	ds_read_b128 v[218:221], v154 offset:4608
	ds_read_b128 v[234:237], v154 offset:64
	ds_read_b128 v[238:241], v154 offset:4672
	ds_read_b128 v[242:245], v154 offset:9216
	ds_read_b128 v[246:249], v154 offset:13824
	ds_read_b128 v[250:253], v154 offset:9280
	v_mad_u64_u32 v[102:103], s[92:93], v94, s58, v[4:5]
	s_waitcnt lgkmcnt(9)
	v_mfma_f32_16x16x32_bf16 v[58:61], v[90:93], v[98:101], v[58:61]
	v_mov_b32_e32 v4, v103
	v_mad_u64_u32 v[94:95], s[92:93], v95, s58, v[4:5]
	v_mov_b32_e32 v103, v94
	ds_read_b128 v[94:97], v154 offset:13888
	v_lshlrev_b64 v[90:91], 1, v[102:103]
	v_lshl_add_u64 v[98:99], s[72:73], 0, v[90:91]
	v_lshl_add_u64 v[100:101], s[74:75], 0, v[90:91]
	v_lshlrev_b64 v[90:91], 10, v[118:119]
	v_or_b32_e32 v90, v90, v124
	global_load_dwordx4 v[114:117], v[98:99], off
	global_load_dwordx4 v[110:113], v[100:101], off
	v_lshl_add_u64 v[98:99], s[16:17], 0, v[90:91]
	v_add_co_u32_e32 v98, vcc, s41, v98
	s_nop 1
	v_addc_co_u32_e32 v99, vcc, -1, v99, vcc
	global_load_dwordx4 v[118:121], v[98:99], off offset:-128
	v_mul_lo_u32 v4, v122, s38
	v_cmp_eq_u32_e32 vcc, 0, v146
	s_waitcnt lgkmcnt(7)
	v_mfma_f32_16x16x32_bf16 v[6:9], v[82:85], v[208:211], v[6:9]
	s_waitcnt lgkmcnt(6)
	v_mfma_f32_16x16x32_bf16 v[14:17], v[82:85], v[218:221], v[14:17]
	s_waitcnt lgkmcnt(5)
	v_mfma_f32_16x16x32_bf16 v[6:9], v[86:89], v[234:237], v[6:9]
	s_waitcnt lgkmcnt(4)
	v_mfma_f32_16x16x32_bf16 v[14:17], v[86:89], v[238:241], v[14:17]
	s_waitcnt lgkmcnt(3)
	v_mfma_f32_16x16x32_bf16 v[22:25], v[82:85], v[242:245], v[22:25]
	s_waitcnt lgkmcnt(2)
	v_mfma_f32_16x16x32_bf16 v[26:29], v[82:85], v[246:249], v[26:29]
	s_waitcnt lgkmcnt(1)
	v_mfma_f32_16x16x32_bf16 v[22:25], v[86:89], v[250:253], v[22:25]
	v_lshlrev_b32_e32 v82, 1, v124
	v_add3_u32 v4, 0, v4, v82
	s_waitcnt lgkmcnt(0)
	v_mfma_f32_16x16x32_bf16 v[26:29], v[86:89], v[94:97], v[26:29]
	ds_read_b128 v[94:97], v4 offset:50176
	ds_read_b128 v[82:85], v4 offset:50192
	v_lshl_add_u32 v4, v124, 2, 0
	v_add_u32_e32 v4, 0x20640, v4
	ds_read_b128 v[102:105], v4
	ds_read_b128 v[98:101], v4 offset:16
	ds_read_b128 v[90:93], v4 offset:32
	ds_read_b128 v[86:89], v4 offset:48
	v_ashrrev_i32_e32 v4, 2, v191
	v_mul_lo_u32 v122, v4, s63
	v_add3_u32 v126, s18, v122, v123
	ds_read_b128 v[122:125], v126
	ds_read_b128 v[126:129], v126 offset:16
	ds_read_b128 v[130:133], v142
	ds_read_b128 v[134:137], v142 offset:16
	ds_read_b128 v[138:141], v142 offset:32
	ds_read_b128 v[142:145], v142 offset:48
	s_waitcnt lgkmcnt(5)
	v_lshlrev_b32_e32 v147, 16, v122
	v_and_b32_e32 v122, 0xffff0000, v122
	s_waitcnt lgkmcnt(3)
	v_mul_f32_e32 v122, v131, v122
	v_fmac_f32_e32 v122, v130, v147
	v_lshlrev_b32_e32 v130, 16, v123
	v_fmac_f32_e32 v122, v132, v130
	v_and_b32_e32 v123, 0xffff0000, v123
	v_fmac_f32_e32 v122, v133, v123
	v_lshlrev_b32_e32 v123, 16, v124
	s_waitcnt lgkmcnt(2)
	v_fmac_f32_e32 v122, v134, v123
	v_and_b32_e32 v123, 0xffff0000, v124
	v_fmac_f32_e32 v122, v135, v123
	v_lshlrev_b32_e32 v123, 16, v125
	v_fmac_f32_e32 v122, v136, v123
	v_and_b32_e32 v123, 0xffff0000, v125
	v_fmac_f32_e32 v122, v137, v123
	v_lshlrev_b32_e32 v123, 16, v126
	s_waitcnt lgkmcnt(1)
	v_fmac_f32_e32 v122, v138, v123
	v_and_b32_e32 v123, 0xffff0000, v126
	v_fmac_f32_e32 v122, v139, v123
	v_lshlrev_b32_e32 v123, 16, v127
	v_fmac_f32_e32 v122, v140, v123
	v_and_b32_e32 v123, 0xffff0000, v127
	v_fmac_f32_e32 v122, v141, v123
	v_lshlrev_b32_e32 v123, 16, v128
	s_waitcnt lgkmcnt(0)
	v_fmac_f32_e32 v122, v142, v123
	v_and_b32_e32 v123, 0xffff0000, v128
	v_fmac_f32_e32 v122, v143, v123
	v_lshlrev_b32_e32 v123, 16, v129
	v_fmac_f32_e32 v122, v144, v123
	v_and_b32_e32 v123, 0xffff0000, v129
	v_fmac_f32_e32 v122, v145, v123
	s_nop 1
	v_add_f32_dpp v122, v122, v122 quad_perm:[1,0,3,2] row_mask:0xf bank_mask:0xf bound_ctrl:1
	s_nop 1
	v_mov_b32_dpp v123, v122 quad_perm:[2,3,0,1] row_mask:0xf bank_mask:0xf bound_ctrl:1
	s_and_saveexec_b64 s[92:93], vcc
	s_cbranch_execz .LBB0_375
	v_lshl_add_u32 v4, v4, 2, 0
	v_add_f32_e32 v122, v122, v123
	v_add_u32_e32 v123, 0x20640, v4
	ds_read_b32 v123, v123
	v_add_u32_e32 v4, 0x20c80, v4
	s_waitcnt lgkmcnt(0)
	v_fmac_f32_e32 v122, v182, v123
	ds_write_b32 v4, v122
